# P3 decay prefix-product pass rewritten by hand with 16-byte loads/stores (one 32-row chunk x 4 columns per lane), plain stores
# speedup vs baseline: 1.0206x; 1.0005x over previous
; __global__ void __launch_bounds__(NWAVES * 64, 2) hybrid_fwd(Args A) {
;     ...
;             for (int u = bx; u < 192; u += G) { const int pm = u / 6, pn = u % 6;
;                 for (int i = 0; i < 4; i += 2) { const size_t base = (size_t)(pm * 256 + (t2 >> 6) * 32) * RW + pn * 256 + (t2 & 63) + 64 * i;
;                     float wv[32], wu[32];
; #pragma unroll
;                     for (int t = 0; t < 32; ++t) { wv[t] = __hip_atomic_load(DEC + base + (size_t)t * RW, __ATOMIC_RELAXED, __HIP_MEMORY_SCOPE_AGENT); wu[t] = __hip_atomic_load(DEC + base + 64 + (size_t)t * RW, __ATOMIC_RELAXED, __HIP_MEMORY_SCOPE_AGENT); }
;                     float gq = 1.f, gu = 1.f;
; #pragma unroll
;                     for (int t = 0; t < 32; ++t) { __builtin_nontemporal_store(gq, &GAME[base + (size_t)t * RW]); gq *= wv[t]; __builtin_nontemporal_store(gu, &GAME[base + 64 + (size_t)t * RW]); gu *= wu[t]; } } }
.LBB0_382:
	s_waitcnt lgkmcnt(0)
	s_waitcnt vmcnt(0)
	s_cmpk_gt_i32 s97, 0xbf
	s_barrier
	v_mbcnt_lo_u32_b32 v0, -1, 0
	v_mbcnt_hi_u32_b32 v0, -1, v0
	s_cbranch_scc1 .LBB0_387
	s_lshr_b32 s0, s36, 1
	s_add_u32 s10, s6, 0x30a00000
	s_addc_u32 s11, s7, 0
	v_and_b32_e32 v0, 63, v0
	v_lshlrev_b32_e32 v1, 4, v0
	s_mov_b32 s65, s97
.Lgm_unit:
	s_mul_hi_i32 s2, s65, 0x2aaaaaab
	s_lshr_b32 s3, s2, 31
	s_add_i32 s2, s2, s3
	s_mul_i32 s3, s2, 6
	s_sub_i32 s3, s65, s3
	s_lshl_b32 s2, s2, 8
	s_add_i32 s2, s2, s0
	s_mul_i32 s2, s2, 0x1800
	s_lshl_b32 s3, s3, 10
	s_add_u32 s2, s2, s3
	s_add_u32 s12, s8, s2
	s_addc_u32 s13, s9, 0
	s_add_u32 s14, s10, s2
	s_addc_u32 s15, s11, 0
	global_load_dwordx4 v[8:11], v1, s[12:13] sc1
	s_add_u32 s12, s12, 0x1800
	s_addc_u32 s13, s13, 0
	global_load_dwordx4 v[12:15], v1, s[12:13] sc1
	s_add_u32 s12, s12, 0x1800
	s_addc_u32 s13, s13, 0
	global_load_dwordx4 v[16:19], v1, s[12:13] sc1
	s_add_u32 s12, s12, 0x1800
	s_addc_u32 s13, s13, 0
	global_load_dwordx4 v[20:23], v1, s[12:13] sc1
	s_add_u32 s12, s12, 0x1800
	s_addc_u32 s13, s13, 0
	global_load_dwordx4 v[24:27], v1, s[12:13] sc1
	s_add_u32 s12, s12, 0x1800
	s_addc_u32 s13, s13, 0
	global_load_dwordx4 v[28:31], v1, s[12:13] sc1
	s_add_u32 s12, s12, 0x1800
	s_addc_u32 s13, s13, 0
	global_load_dwordx4 v[32:35], v1, s[12:13] sc1
	s_add_u32 s12, s12, 0x1800
	s_addc_u32 s13, s13, 0
	global_load_dwordx4 v[36:39], v1, s[12:13] sc1
	s_add_u32 s12, s12, 0x1800
	s_addc_u32 s13, s13, 0
	global_load_dwordx4 v[40:43], v1, s[12:13] sc1
	s_add_u32 s12, s12, 0x1800
	s_addc_u32 s13, s13, 0
	global_load_dwordx4 v[44:47], v1, s[12:13] sc1
	s_add_u32 s12, s12, 0x1800
	s_addc_u32 s13, s13, 0
	global_load_dwordx4 v[48:51], v1, s[12:13] sc1
	s_add_u32 s12, s12, 0x1800
	s_addc_u32 s13, s13, 0
	global_load_dwordx4 v[52:55], v1, s[12:13] sc1
	s_add_u32 s12, s12, 0x1800
	s_addc_u32 s13, s13, 0
	global_load_dwordx4 v[56:59], v1, s[12:13] sc1
	s_add_u32 s12, s12, 0x1800
	s_addc_u32 s13, s13, 0
	global_load_dwordx4 v[60:63], v1, s[12:13] sc1
	s_add_u32 s12, s12, 0x1800
	s_addc_u32 s13, s13, 0
	global_load_dwordx4 v[64:67], v1, s[12:13] sc1
	s_add_u32 s12, s12, 0x1800
	s_addc_u32 s13, s13, 0
	global_load_dwordx4 v[68:71], v1, s[12:13] sc1
	s_add_u32 s12, s12, 0x1800
	s_addc_u32 s13, s13, 0
	global_load_dwordx4 v[72:75], v1, s[12:13] sc1
	s_add_u32 s12, s12, 0x1800
	s_addc_u32 s13, s13, 0
	global_load_dwordx4 v[76:79], v1, s[12:13] sc1
	s_add_u32 s12, s12, 0x1800
	s_addc_u32 s13, s13, 0
	global_load_dwordx4 v[80:83], v1, s[12:13] sc1
	s_add_u32 s12, s12, 0x1800
	s_addc_u32 s13, s13, 0
	global_load_dwordx4 v[84:87], v1, s[12:13] sc1
	s_add_u32 s12, s12, 0x1800
	s_addc_u32 s13, s13, 0
	global_load_dwordx4 v[88:91], v1, s[12:13] sc1
	s_add_u32 s12, s12, 0x1800
	s_addc_u32 s13, s13, 0
	global_load_dwordx4 v[92:95], v1, s[12:13] sc1
	s_add_u32 s12, s12, 0x1800
	s_addc_u32 s13, s13, 0
	global_load_dwordx4 v[96:99], v1, s[12:13] sc1
	s_add_u32 s12, s12, 0x1800
	s_addc_u32 s13, s13, 0
	global_load_dwordx4 v[100:103], v1, s[12:13] sc1
	s_add_u32 s12, s12, 0x1800
	s_addc_u32 s13, s13, 0
	global_load_dwordx4 v[104:107], v1, s[12:13] sc1
	s_add_u32 s12, s12, 0x1800
	s_addc_u32 s13, s13, 0
	global_load_dwordx4 v[108:111], v1, s[12:13] sc1
	s_add_u32 s12, s12, 0x1800
	s_addc_u32 s13, s13, 0
	global_load_dwordx4 v[112:115], v1, s[12:13] sc1
	s_add_u32 s12, s12, 0x1800
	s_addc_u32 s13, s13, 0
	global_load_dwordx4 v[116:119], v1, s[12:13] sc1
	s_add_u32 s12, s12, 0x1800
	s_addc_u32 s13, s13, 0
	global_load_dwordx4 v[120:123], v1, s[12:13] sc1
	s_add_u32 s12, s12, 0x1800
	s_addc_u32 s13, s13, 0
	global_load_dwordx4 v[124:127], v1, s[12:13] sc1
	s_add_u32 s12, s12, 0x1800
	s_addc_u32 s13, s13, 0
	global_load_dwordx4 v[128:131], v1, s[12:13] sc1
	s_add_u32 s12, s12, 0x1800
	s_addc_u32 s13, s13, 0
	global_load_dwordx4 v[132:135], v1, s[12:13] sc1
	v_mov_b32_e32 v2, 1.0
	v_mov_b32_e32 v3, 1.0
	v_mov_b32_e32 v4, 1.0
	v_mov_b32_e32 v5, 1.0
	global_store_dwordx4 v1, v[2:5], s[14:15]
	s_add_u32 s14, s14, 0x1800
	s_addc_u32 s15, s15, 0
	s_waitcnt vmcnt(32)
	v_mul_f32_e32 v2, v2, v8
	v_mul_f32_e32 v3, v3, v9
	v_mul_f32_e32 v4, v4, v10
	v_mul_f32_e32 v5, v5, v11
	global_store_dwordx4 v1, v[2:5], s[14:15]
	s_add_u32 s14, s14, 0x1800
	s_addc_u32 s15, s15, 0
	s_waitcnt vmcnt(32)
	v_mul_f32_e32 v2, v2, v12
	v_mul_f32_e32 v3, v3, v13
	v_mul_f32_e32 v4, v4, v14
	v_mul_f32_e32 v5, v5, v15
	global_store_dwordx4 v1, v[2:5], s[14:15]
	s_add_u32 s14, s14, 0x1800
	s_addc_u32 s15, s15, 0
	s_waitcnt vmcnt(32)
	v_mul_f32_e32 v2, v2, v16
	v_mul_f32_e32 v3, v3, v17
	v_mul_f32_e32 v4, v4, v18
	v_mul_f32_e32 v5, v5, v19
	global_store_dwordx4 v1, v[2:5], s[14:15]
	s_add_u32 s14, s14, 0x1800
	s_addc_u32 s15, s15, 0
	s_waitcnt vmcnt(32)
	v_mul_f32_e32 v2, v2, v20
	v_mul_f32_e32 v3, v3, v21
	v_mul_f32_e32 v4, v4, v22
	v_mul_f32_e32 v5, v5, v23
	global_store_dwordx4 v1, v[2:5], s[14:15]
	s_add_u32 s14, s14, 0x1800
	s_addc_u32 s15, s15, 0
	s_waitcnt vmcnt(32)
	v_mul_f32_e32 v2, v2, v24
	v_mul_f32_e32 v3, v3, v25
	v_mul_f32_e32 v4, v4, v26
	v_mul_f32_e32 v5, v5, v27
	global_store_dwordx4 v1, v[2:5], s[14:15]
	s_add_u32 s14, s14, 0x1800
	s_addc_u32 s15, s15, 0
	s_waitcnt vmcnt(32)
	v_mul_f32_e32 v2, v2, v28
	v_mul_f32_e32 v3, v3, v29
	v_mul_f32_e32 v4, v4, v30
	v_mul_f32_e32 v5, v5, v31
	global_store_dwordx4 v1, v[2:5], s[14:15]
	s_add_u32 s14, s14, 0x1800
	s_addc_u32 s15, s15, 0
	s_waitcnt vmcnt(32)
	v_mul_f32_e32 v2, v2, v32
	v_mul_f32_e32 v3, v3, v33
	v_mul_f32_e32 v4, v4, v34
	v_mul_f32_e32 v5, v5, v35
	global_store_dwordx4 v1, v[2:5], s[14:15]
	s_add_u32 s14, s14, 0x1800
	s_addc_u32 s15, s15, 0
	s_waitcnt vmcnt(32)
; __global__ void __launch_bounds__(NWAVES * 64, 2) hybrid_fwd(Args A) {
;     ...
;                     for (int t = 0; t < 32; ++t) { wv[t] = __hip_atomic_load(DEC + base + (size_t)t * RW, __ATOMIC_RELAXED, __HIP_MEMORY_SCOPE_AGENT); wu[t] = __hip_atomic_load(DEC + base + 64 + (size_t)t * RW, __ATOMIC_RELAXED, __HIP_MEMORY_SCOPE_AGENT); }
;                     float gq = 1.f, gu = 1.f;
; #pragma unroll
;                     for (int t = 0; t < 32; ++t) { __builtin_nontemporal_store(gq, &GAME[base + (size_t)t * RW]); gq *= wv[t]; __builtin_nontemporal_store(gu, &GAME[base + 64 + (size_t)t * RW]); gu *= wu[t]; } } }
	v_mul_f32_e32 v2, v2, v36
	v_mul_f32_e32 v3, v3, v37
	v_mul_f32_e32 v4, v4, v38
	v_mul_f32_e32 v5, v5, v39
	global_store_dwordx4 v1, v[2:5], s[14:15]
	s_add_u32 s14, s14, 0x1800
	s_addc_u32 s15, s15, 0
	s_waitcnt vmcnt(32)
	v_mul_f32_e32 v2, v2, v40
	v_mul_f32_e32 v3, v3, v41
	v_mul_f32_e32 v4, v4, v42
	v_mul_f32_e32 v5, v5, v43
	global_store_dwordx4 v1, v[2:5], s[14:15]
	s_add_u32 s14, s14, 0x1800
	s_addc_u32 s15, s15, 0
	s_waitcnt vmcnt(32)
	v_mul_f32_e32 v2, v2, v44
	v_mul_f32_e32 v3, v3, v45
	v_mul_f32_e32 v4, v4, v46
	v_mul_f32_e32 v5, v5, v47
	global_store_dwordx4 v1, v[2:5], s[14:15]
	s_add_u32 s14, s14, 0x1800
	s_addc_u32 s15, s15, 0
	s_waitcnt vmcnt(32)
	v_mul_f32_e32 v2, v2, v48
	v_mul_f32_e32 v3, v3, v49
	v_mul_f32_e32 v4, v4, v50
	v_mul_f32_e32 v5, v5, v51
	global_store_dwordx4 v1, v[2:5], s[14:15]
	s_add_u32 s14, s14, 0x1800
	s_addc_u32 s15, s15, 0
	s_waitcnt vmcnt(32)
	v_mul_f32_e32 v2, v2, v52
	v_mul_f32_e32 v3, v3, v53
	v_mul_f32_e32 v4, v4, v54
	v_mul_f32_e32 v5, v5, v55
	global_store_dwordx4 v1, v[2:5], s[14:15]
	s_add_u32 s14, s14, 0x1800
	s_addc_u32 s15, s15, 0
	s_waitcnt vmcnt(32)
	v_mul_f32_e32 v2, v2, v56
	v_mul_f32_e32 v3, v3, v57
	v_mul_f32_e32 v4, v4, v58
	v_mul_f32_e32 v5, v5, v59
	global_store_dwordx4 v1, v[2:5], s[14:15]
	s_add_u32 s14, s14, 0x1800
	s_addc_u32 s15, s15, 0
	s_waitcnt vmcnt(32)
	v_mul_f32_e32 v2, v2, v60
	v_mul_f32_e32 v3, v3, v61
	v_mul_f32_e32 v4, v4, v62
	v_mul_f32_e32 v5, v5, v63
	global_store_dwordx4 v1, v[2:5], s[14:15]
	s_add_u32 s14, s14, 0x1800
	s_addc_u32 s15, s15, 0
	s_waitcnt vmcnt(32)
	v_mul_f32_e32 v2, v2, v64
	v_mul_f32_e32 v3, v3, v65
	v_mul_f32_e32 v4, v4, v66
	v_mul_f32_e32 v5, v5, v67
	global_store_dwordx4 v1, v[2:5], s[14:15]
	s_add_u32 s14, s14, 0x1800
	s_addc_u32 s15, s15, 0
	s_waitcnt vmcnt(32)
	v_mul_f32_e32 v2, v2, v68
	v_mul_f32_e32 v3, v3, v69
	v_mul_f32_e32 v4, v4, v70
	v_mul_f32_e32 v5, v5, v71
	global_store_dwordx4 v1, v[2:5], s[14:15]
	s_add_u32 s14, s14, 0x1800
	s_addc_u32 s15, s15, 0
	s_waitcnt vmcnt(32)
	v_mul_f32_e32 v2, v2, v72
	v_mul_f32_e32 v3, v3, v73
	v_mul_f32_e32 v4, v4, v74
	v_mul_f32_e32 v5, v5, v75
	global_store_dwordx4 v1, v[2:5], s[14:15]
	s_add_u32 s14, s14, 0x1800
	s_addc_u32 s15, s15, 0
	s_waitcnt vmcnt(32)
	v_mul_f32_e32 v2, v2, v76
	v_mul_f32_e32 v3, v3, v77
	v_mul_f32_e32 v4, v4, v78
	v_mul_f32_e32 v5, v5, v79
	global_store_dwordx4 v1, v[2:5], s[14:15]
	s_add_u32 s14, s14, 0x1800
	s_addc_u32 s15, s15, 0
	s_waitcnt vmcnt(32)
	v_mul_f32_e32 v2, v2, v80
	v_mul_f32_e32 v3, v3, v81
	v_mul_f32_e32 v4, v4, v82
	v_mul_f32_e32 v5, v5, v83
	global_store_dwordx4 v1, v[2:5], s[14:15]
	s_add_u32 s14, s14, 0x1800
	s_addc_u32 s15, s15, 0
	s_waitcnt vmcnt(32)
	v_mul_f32_e32 v2, v2, v84
	v_mul_f32_e32 v3, v3, v85
	v_mul_f32_e32 v4, v4, v86
	v_mul_f32_e32 v5, v5, v87
	global_store_dwordx4 v1, v[2:5], s[14:15]
	s_add_u32 s14, s14, 0x1800
	s_addc_u32 s15, s15, 0
	s_waitcnt vmcnt(32)
	v_mul_f32_e32 v2, v2, v88
	v_mul_f32_e32 v3, v3, v89
	v_mul_f32_e32 v4, v4, v90
	v_mul_f32_e32 v5, v5, v91
	global_store_dwordx4 v1, v[2:5], s[14:15]
	s_add_u32 s14, s14, 0x1800
	s_addc_u32 s15, s15, 0
	s_waitcnt vmcnt(32)
	v_mul_f32_e32 v2, v2, v92
	v_mul_f32_e32 v3, v3, v93
	v_mul_f32_e32 v4, v4, v94
	v_mul_f32_e32 v5, v5, v95
	global_store_dwordx4 v1, v[2:5], s[14:15]
	s_add_u32 s14, s14, 0x1800
	s_addc_u32 s15, s15, 0
	s_waitcnt vmcnt(32)
	v_mul_f32_e32 v2, v2, v96
	v_mul_f32_e32 v3, v3, v97
	v_mul_f32_e32 v4, v4, v98
	v_mul_f32_e32 v5, v5, v99
	global_store_dwordx4 v1, v[2:5], s[14:15]
	s_add_u32 s14, s14, 0x1800
	s_addc_u32 s15, s15, 0
	s_waitcnt vmcnt(32)
	v_mul_f32_e32 v2, v2, v100
	v_mul_f32_e32 v3, v3, v101
	v_mul_f32_e32 v4, v4, v102
	v_mul_f32_e32 v5, v5, v103
	global_store_dwordx4 v1, v[2:5], s[14:15]
	s_add_u32 s14, s14, 0x1800
	s_addc_u32 s15, s15, 0
	s_waitcnt vmcnt(32)
	v_mul_f32_e32 v2, v2, v104
	v_mul_f32_e32 v3, v3, v105
	v_mul_f32_e32 v4, v4, v106
	v_mul_f32_e32 v5, v5, v107
	global_store_dwordx4 v1, v[2:5], s[14:15]
	s_add_u32 s14, s14, 0x1800
	s_addc_u32 s15, s15, 0
	s_waitcnt vmcnt(32)
	v_mul_f32_e32 v2, v2, v108
	v_mul_f32_e32 v3, v3, v109
	v_mul_f32_e32 v4, v4, v110
	v_mul_f32_e32 v5, v5, v111
	global_store_dwordx4 v1, v[2:5], s[14:15]
	s_add_u32 s14, s14, 0x1800
	s_addc_u32 s15, s15, 0
	s_waitcnt vmcnt(32)
	v_mul_f32_e32 v2, v2, v112
	v_mul_f32_e32 v3, v3, v113
	v_mul_f32_e32 v4, v4, v114
	v_mul_f32_e32 v5, v5, v115
	global_store_dwordx4 v1, v[2:5], s[14:15]
	s_add_u32 s14, s14, 0x1800
	s_addc_u32 s15, s15, 0
	s_waitcnt vmcnt(32)
	v_mul_f32_e32 v2, v2, v116
	v_mul_f32_e32 v3, v3, v117
	v_mul_f32_e32 v4, v4, v118
	v_mul_f32_e32 v5, v5, v119
	global_store_dwordx4 v1, v[2:5], s[14:15]
	s_add_u32 s14, s14, 0x1800
	s_addc_u32 s15, s15, 0
	s_waitcnt vmcnt(32)
	v_mul_f32_e32 v2, v2, v120
	v_mul_f32_e32 v3, v3, v121
	v_mul_f32_e32 v4, v4, v122
	v_mul_f32_e32 v5, v5, v123
	global_store_dwordx4 v1, v[2:5], s[14:15]
	s_add_u32 s14, s14, 0x1800
	s_addc_u32 s15, s15, 0
	s_waitcnt vmcnt(32)
	v_mul_f32_e32 v2, v2, v124
	v_mul_f32_e32 v3, v3, v125
	v_mul_f32_e32 v4, v4, v126
	v_mul_f32_e32 v5, v5, v127
	global_store_dwordx4 v1, v[2:5], s[14:15]
	s_add_u32 s14, s14, 0x1800
	s_addc_u32 s15, s15, 0
	s_waitcnt vmcnt(32)
	v_mul_f32_e32 v2, v2, v128
	v_mul_f32_e32 v3, v3, v129
	v_mul_f32_e32 v4, v4, v130
	v_mul_f32_e32 v5, v5, v131
	global_store_dwordx4 v1, v[2:5], s[14:15]
	s_add_i32 s65, s65, s31
	s_cmpk_lt_i32 s65, 0xc0
	s_cbranch_scc1 .Lgm_unit
